# barrier-shadow touches: next weight tile + fused-LN gamma/beta columns + projection bias vector lines (small, cold input data on epilogue critical paths)
# speedup vs baseline: 1.0063x; 1.0063x over previous
; #define GRID_BAR() xcd_barrier(bar)
; __global__ void __launch_bounds__(NTHREADS, 2) mk_fwd(Args args) {
;     ...
;         const int layer = step == 0 ? 0 : (step - 1) / 6, s6 = step == 0 ? -1 : (step - 1) % 6;
;         const int st = s6 < 0 ? 0 : (s6 < 4 ? s6 + 1 : (s6 == 4 ? 6 : 8));
;     ...
;         if (step + 1 < NSTEPS) {
;             if (st == 1 || st == 2 || st == 3) xcd_barrier_arrive(bar);
;             else GRID_BAR();
.Ltch_full:
	s_cmp_eq_u32 s91, 3
	s_cbranch_scc1 .Ltch_d_a
	s_cmp_eq_u32 s91, 4
	s_cbranch_scc1 .Ltch_e_a
	s_cmp_eq_u32 s91, 6
	s_cbranch_scc1 .Ltch_f_a
	s_cmp_eq_u32 s91, 2
	s_cbranch_scc1 .Ltch_c_a
	s_cmp_eq_u32 s91, 0
	s_cbranch_scc1 .Ltch_w_a
	s_cmp_eq_u32 s91, 8
	s_cbranch_scc1 .Ltch_a_a
	s_branch .LBB0_763

;     __device__ __forceinline__ void fused(f32x4 (&acc)[2][2][4][2], const GUnit& u, int wr, int wc, int fr, int fq, LAS unsigned char* lds, int wid, int lane) const {
;     ...
;         for (int bj = 0; bj < 2; ++bj)
; #pragma unroll
;             for (int n = 0; n < 2; ++n) { gv[bj][n] = *(const f32x4*)(ln_g + gcol0 + bj * 128 + 4 * n); bv[bj][n] = *(const f32x4*)(ln_b + gcol0 + bj * 128 + 4 * n); }
.Ltch_t2_da:
	s_or_b64 exec, exec, s[4:5]
	v_cmp_gt_u32_e32 vcc, 8, v245
	s_and_saveexec_b64 s[4:5], vcc
	s_cbranch_execz .Ltch_g2_da
	v_readlane_b32 s8, v254, 60
	v_readlane_b32 s9, v254, 61
	v_readlane_b32 s6, v253, 18
	s_lshl_b32 s7, s72, 12
	s_lshl_b32 s6, s6, 10
	s_add_i32 s7, s7, s6
	v_lshl_add_u32 v246, v245, 7, s7
	s_load_dwordx2 s[6:7], s[8:9], 0x60
	s_waitcnt lgkmcnt(0)
	s_nop 0
	global_load_dword v244, v246, s[6:7]
	s_load_dwordx2 s[6:7], s[8:9], 0x68
	s_waitcnt lgkmcnt(0)
	s_nop 0
	global_load_dword v244, v246, s[6:7]

;     __device__ __forceinline__ bool next_(int i, GUnit& u) const {
;     ...
;         } else if (phase == PH_E) {
;             if (c >= 128 && i < 2) { int pm, pn; pg8::tile_order(64, 4, c, pm, pn); pn = 2 * (pn - 2) + i; u.pm = pm; u.pn = pn;
;                 u.K = 256; u.A = w + WS_P16 + (size_t)pm * 256 * 256 * 2; u.B = w + W_P + (size_t)pn * 256 * 256 * 2; u.kind = K_PP;
;                 return true; }
;             const int L = (c >= 128 ? i - 2 : i) * G + c; if (L >= 1408) return false;
;             int pm, pn; pg8::tile_order(64, 22, L, pm, pn); u.pm = pm; u.pn = pn; u.K = 1024;
;             u.A = w + WS_H16 + (size_t)pm * 256 * 1024 * 2; u.B = w + W_UP + (size_t)pn * 128 * 1024 * 2; u.bhs = (size_t)DFF * 1024 * 2; u.kind = K_FFN; return true;
.Ltch_ego_a:
	v_mov_b32_e32 v248, s9
	v_lshrrev_b32_e32 v246, 1, v245
	v_and_b32_e32 v247, 1, v245
	v_cmp_lt_u32_e32 vcc, 0x7f, v246
	v_lshlrev_b32_e32 v246, s8, v246
	v_lshl_add_u32 v246, v247, 7, v246
	v_cndmask_b32_e32 v247, 0, v248, vcc
	v_add_u32_e32 v246, v246, v247
	s_nop 0
	global_load_dword v244, v246, s[6:7]
	v_cmp_gt_u32_e32 vcc, 64, v245
	s_and_saveexec_b64 s[4:5], vcc
	s_cbranch_execz .Ltch_t2_ea
	v_add_u32_e32 v249, 0x1c0, v245
	v_lshrrev_b32_e32 v246, 1, v249
	v_and_b32_e32 v247, 1, v249
	v_lshlrev_b32_e32 v246, s8, v246
	v_lshl_add_u32 v246, v247, 7, v246
	v_add_u32_e32 v246, v246, v248
	s_nop 0
	global_load_dword v244, v246, s[6:7]
.Ltch_t2_ea:
	s_or_b64 exec, exec, s[4:5]
	s_branch .LBB0_763

;     __device__ __forceinline__ void fused(f32x4 (&acc)[2][2][4][2], const GUnit& u, int wr, int wc, int fr, int fq, LAS unsigned char* lds, int wid, int lane) const {
;     ...
;         for (int bj = 0; bj < 2; ++bj)
; #pragma unroll
;             for (int n = 0; n < 2; ++n) { gv[bj][n] = *(const f32x4*)(ln_g + gcol0 + bj * 128 + 4 * n); bv[bj][n] = *(const f32x4*)(ln_b + gcol0 + bj * 128 + 4 * n); }
.Ltch_t2_fa:
	s_or_b64 exec, exec, s[4:5]
	v_cmp_gt_u32_e32 vcc, 8, v245
	s_and_saveexec_b64 s[4:5], vcc
	s_cbranch_execz .Ltch_g2_fa
	v_readlane_b32 s8, v254, 60
	v_readlane_b32 s9, v254, 61
	v_readlane_b32 s6, v253, 18
	s_lshl_b32 s7, s72, 12
	s_lshl_b32 s6, s6, 10
	s_add_i32 s7, s7, s6
	v_lshl_add_u32 v246, v245, 7, s7
	s_load_dwordx2 s[6:7], s[8:9], 0xa0
	s_waitcnt lgkmcnt(0)
	s_nop 0
	global_load_dword v244, v246, s[6:7]
	s_load_dwordx2 s[6:7], s[8:9], 0xa8
	s_waitcnt lgkmcnt(0)
	s_nop 0
	global_load_dword v244, v246, s[6:7]

;     __device__ __forceinline__ void operator()(const f32x4 (&acc)[2][2][4][2], const GUnit& u, int wr, int wc, int fr, int fq, LAS unsigned char*) const {
;     ...
;         unsigned char* base = ws + B_SG; const float* bias = b_in + gcol0;
;         f32x4 bv[2][2];
;         const bool qk = u.kind != K_SG;
; #pragma unroll
;         for (int bj = 0; bj < 2; ++bj)
; #pragma unroll
;             for (int n = 0; n < 2; ++n) bv[bj][n] = *(const f32x4*)(bias + bj * 128 + 4 * n);
.Ltch_c_a:
	v_readlane_b32 s5, v254, 6
	v_mbcnt_lo_u32_b32 v245, -1, 0
	v_mbcnt_hi_u32_b32 v245, -1, v245
	s_add_i32 s5, s5, -1
	s_lshl_b32 s5, s5, 6
	s_nop 0
	v_add_u32_e32 v245, s5, v245
	v_cmp_gt_u32_e32 vcc, 0x40, v245
	s_and_saveexec_b64 s[4:5], vcc
	s_cbranch_execz .Ltch_b2_ca
	v_readlane_b32 s8, v254, 60
	v_readlane_b32 s9, v254, 61
	s_add_i32 s7, s72, 0
	s_lshl_b32 s7, s7, 14
	s_add_i32 s7, s7, 0x2000
	v_lshl_add_u32 v246, v245, 7, s7
	s_load_dwordx2 s[6:7], s[8:9], 0x28
	s_waitcnt lgkmcnt(0)
	s_nop 0
	global_load_dword v244, v246, s[6:7]

; __global__ void __launch_bounds__(NTHREADS, 2) mk_fwd(Args args) {
;     ...
;             const Sched S8{st == 1 ? PH_AQ : PH_A8, bx, G, ws, layer & 1, wave0}; const EpiGate EG{ws, args.in[5] + (size_t)layer * NPROJ, 0};
;             pg8::gemm_phase<true>(lds, S8, EG);
;         }
;         if (st == 2 || st == 3 || st == 4) xcd_barrier_wait(bar);
;         if (st == 1 || st == 3 || st == 4 || st == 6 || st == 8) {
;             const int ph = st == 1 ? PH_A : (st == 3 ? PH_C : (st == 4 ? PH_D : (st == 6 ? PH_E : PH_F)));
;             const Epi E{ws, out, args.in[5] + (size_t)layer * NPROJ, args.in[st == 4 ? 12 : 20] + (size_t)layer * DM, args.in[st == 4 ? 13 : 21] + (size_t)layer * DM,
;                         (unsigned*)(ws + WS_CTL) + CW_SEAM + (2 * layer + (st == 4 ? 0 : 1)) * SEAM_BANK, args.in[15] + (size_t)layer * 3 * DFF, args.in[16] + (size_t)layer * DFF, 0, (layer == DEPTH - 1 && st == 8) ? 1 : 0, st == 8 ? 1 : 0};
.Ltch_w_a:
	v_readlane_b32 s5, v254, 6
	v_mbcnt_lo_u32_b32 v245, -1, 0
	v_mbcnt_hi_u32_b32 v245, -1, v245
	s_add_i32 s5, s5, -1
	s_lshl_b32 s5, s5, 6
	s_nop 0
	v_add_u32_e32 v245, s5, v245
	v_cmp_gt_u32_e32 vcc, 0x80, v245
	s_and_saveexec_b64 s[4:5], vcc
	s_cbranch_execz .Ltch_b2_wa
	v_readlane_b32 s8, v254, 60
	v_readlane_b32 s9, v254, 61
	s_add_i32 s7, s72, 0
	s_lshl_b32 s7, s7, 14
	s_add_i32 s7, s7, 0x0
	v_lshl_add_u32 v246, v245, 7, s7
	s_load_dwordx2 s[6:7], s[8:9], 0x28
	s_waitcnt lgkmcnt(0)
	s_nop 0
	global_load_dword v244, v246, s[6:7]

; __global__ void __launch_bounds__(NTHREADS, 2) mk_fwd(Args args) {
;     ...
;             const Sched S8{st == 1 ? PH_AQ : PH_A8, bx, G, ws, layer & 1, wave0}; const EpiGate EG{ws, args.in[5] + (size_t)layer * NPROJ, 0};
;             pg8::gemm_phase<true>(lds, S8, EG);
;         }
;         if (st == 2 || st == 3 || st == 4) xcd_barrier_wait(bar);
;         if (st == 1 || st == 3 || st == 4 || st == 6 || st == 8) {
;             const int ph = st == 1 ? PH_A : (st == 3 ? PH_C : (st == 4 ? PH_D : (st == 6 ? PH_E : PH_F)));
;             const Epi E{ws, out, args.in[5] + (size_t)layer * NPROJ, args.in[st == 4 ? 12 : 20] + (size_t)layer * DM, args.in[st == 4 ? 13 : 21] + (size_t)layer * DM,
;                         (unsigned*)(ws + WS_CTL) + CW_SEAM + (2 * layer + (st == 4 ? 0 : 1)) * SEAM_BANK, args.in[15] + (size_t)layer * 3 * DFF, args.in[16] + (size_t)layer * DFF, 0, (layer == DEPTH - 1 && st == 8) ? 1 : 0, st == 8 ? 1 : 0};
.Ltch_a_a:
	s_cmp_eq_u32 s72, 3
	s_cbranch_scc1 .LBB0_763
	v_readlane_b32 s5, v254, 6
	v_mbcnt_lo_u32_b32 v245, -1, 0
	v_mbcnt_hi_u32_b32 v245, -1, v245
	s_add_i32 s5, s5, -1
	s_lshl_b32 s5, s5, 6
	s_nop 0
	v_add_u32_e32 v245, s5, v245
	v_cmp_gt_u32_e32 vcc, 0x80, v245
	s_and_saveexec_b64 s[4:5], vcc
	s_cbranch_execz .Ltch_b2_aa
	v_readlane_b32 s8, v254, 60
	v_readlane_b32 s9, v254, 61
	s_add_i32 s7, s72, 1
	s_lshl_b32 s7, s7, 14
	s_add_i32 s7, s7, 0x0
	v_lshl_add_u32 v246, v245, 7, s7
	s_load_dwordx2 s[6:7], s[8:9], 0x28
	s_waitcnt lgkmcnt(0)
	s_nop 0
	global_load_dword v244, v246, s[6:7]

;     __device__ __forceinline__ bool next_(int i, GUnit& u) const {
;     ...
;         } else if (phase == PH_E) {
;             if (c >= 128 && i < 2) { int pm, pn; pg8::tile_order(64, 4, c, pm, pn); pn = 2 * (pn - 2) + i; u.pm = pm; u.pn = pn;
;                 u.K = 256; u.A = w + WS_P16 + (size_t)pm * 256 * 256 * 2; u.B = w + W_P + (size_t)pn * 256 * 256 * 2; u.kind = K_PP;
;                 return true; }
;             const int L = (c >= 128 ? i - 2 : i) * G + c; if (L >= 1408) return false;
;             int pm, pn; pg8::tile_order(64, 22, L, pm, pn); u.pm = pm; u.pn = pn; u.K = 1024;
;             u.A = w + WS_H16 + (size_t)pm * 256 * 1024 * 2; u.B = w + W_UP + (size_t)pn * 128 * 1024 * 2; u.bhs = (size_t)DFF * 1024 * 2; u.kind = K_FFN; return true;
.Ltch_ego_b:
	v_mov_b32_e32 v248, s9
	v_lshrrev_b32_e32 v246, 1, v245
	v_and_b32_e32 v247, 1, v245
	v_cmp_lt_u32_e32 vcc, 0x7f, v246
	v_lshlrev_b32_e32 v246, s8, v246
	v_lshl_add_u32 v246, v247, 7, v246
	v_cndmask_b32_e32 v247, 0, v248, vcc
	v_add_u32_e32 v246, v246, v247
	s_nop 0
	global_load_dword v244, v246, s[6:7]
	v_cmp_gt_u32_e32 vcc, 64, v245
	s_and_saveexec_b64 s[4:5], vcc
	s_cbranch_execz .Ltch_t2_eb
	v_add_u32_e32 v249, 0x1c0, v245
	v_lshrrev_b32_e32 v246, 1, v249
	v_and_b32_e32 v247, 1, v249
	v_lshlrev_b32_e32 v246, s8, v246
	v_lshl_add_u32 v246, v247, 7, v246
	v_add_u32_e32 v246, v246, v248
	s_nop 0
	global_load_dword v244, v246, s[6:7]
.Ltch_t2_eb:
	s_or_b64 exec, exec, s[4:5]
	s_branch .LBB0_777
